# PREP ret_kv: next unit's K/V tile loads issued right after the current unit's LDS transposition (prefetch into spare registers)
# baseline (speedup 1.0000x reference)
; #define LAS __attribute__((address_space(3)))
; __device__ __forceinline__ unsigned cvt_pk_bf16(float lo, float hi) { unsigned r; asm("v_cvt_pk_bf16_f32 %0, %1, %2" : "=v"(r) : "v"(lo), "v"(hi)); return r; }
; __device__ __forceinline__ float bf2f(unsigned short x) { return __uint_as_float(((unsigned)x) << 16); }
; __device__ __forceinline__ void ret_stage(const Frame& F, int b, int h, int n, bool full, float lg) {
;     LAS unsigned char* L = F.lds;
;     const int tk = F.tid >> 2, part = F.tid & 3;
;     const size_t rowoff = (((size_t)b * 4 + h) * S + n * 128 + tk) * 64 + part * 16;
;     const u32x4* kp = (const u32x4*)((const bf16*)(F.ws + WS_PRK) + rowoff);
;     const u32x4* vp = (const u32x4*)((const bf16*)(F.ws + WS_PRV) + rowoff);
;     const u32x4 k0 = kp[0], k1 = kp[1], v0 = vp[0], v1 = vp[1];
;     if (full) { const u32x4* qp = (const u32x4*)((const bf16*)(F.ws + WS_PRQ) + rowoff);
;         const u32x4 q0 = qp[0], q1 = qp[1];
;         *(LAS u32x4*)(L + RL_Q + tk * 128 + part * 32) = q0; *(LAS u32x4*)(L + RL_Q + tk * 128 + part * 32 + 16) = q1;
;         *(LAS u32x4*)(L + RL_K + tk * 128 + part * 32) = k0; *(LAS u32x4*)(L + RL_K + tk * 128 + part * 32 + 16) = k1; }
;     const float kd = expf((float)(127 - tk) * lg);
;     const unsigned kw[8] = {k0.x, k0.y, k0.z, k0.w, k1.x, k1.y, k1.z, k1.w}, vw[8] = {v0.x, v0.y, v0.z, v0.w, v1.x, v1.y, v1.z, v1.w};
; #pragma unroll
;     for (int i = 0; i < 8; ++i) { const int d = part * 16 + 2 * i;
;         if (!full) { const unsigned pk = cvt_pk_bf16(bf2f((unsigned short)(kw[i] & 0xffffu)) * kd, bf2f((unsigned short)(kw[i] >> 16)) * kd);
;             *(LAS unsigned short*)(L + RL_KT + (d * 128 + tk) * 2) = (unsigned short)(pk & 0xffffu); *(LAS unsigned short*)(L + RL_KT + ((d + 1) * 128 + tk) * 2) = (unsigned short)(pk >> 16); }
;         *(LAS unsigned short*)(L + RL_VT + (d * 128 + tk) * 2) = (unsigned short)(vw[i] & 0xffffu); *(LAS unsigned short*)(L + RL_VT + ((d + 1) * 128 + tk) * 2) = (unsigned short)(vw[i] >> 16); }
; }
; __device__ __forceinline__ void ret_kv_unit(const Frame& F, int unit) {
;     const int n = unit & 15, h = (unit >> 4) & 3, b = unit >> 6;
;     const float lg = c_log_gamma[h];
;     LAS unsigned char* L = F.lds;
;     __syncthreads();
;     ret_stage(F, b, h, n, false, lg);
;     __syncthreads();
.LBB0_1335:
	s_bfe_u32 s6, s4, 0x20004
	s_and_b32 s5, s4, 15
	s_ashr_i32 s26, s4, 6
	s_lshl_b32 s7, s6, 2
	s_getpc_b64 s[10:11]
	s_add_u32 s10, s10, c_log_gamma@rel32@lo+4
	s_addc_u32 s11, s11, c_log_gamma@rel32@hi+12
	s_ashr_i32 s27, s26, 31
	s_load_dword s7, s[10:11], s7 offset:0x0
	s_lshl_b64 s[10:11], s[26:27], 13
	s_lshl_b32 s9, s6, 11
	s_lshl_b32 s30, s5, 7
	s_or_b32 s9, s10, s9
	s_or_b32 s10, s9, s30
	v_lshl_add_u64 v[20:21], s[10:11], 0, v[2:3]
	v_lshlrev_b64 v[20:21], 7, v[20:21]
	v_lshl_or_b32 v20, v4, 1, v20
	s_waitcnt vmcnt(20)
	v_lshl_add_u64 v[24:25], s[0:1], 0, v[20:21]
	s_waitcnt lgkmcnt(0)
	s_barrier
	s_waitcnt vmcnt(16)
	v_lshl_add_u64 v[32:33], s[14:15], 0, v[20:21]
	global_load_dwordx4 v[20:23], v[24:25], off offset:16
	s_nop 0
	global_load_dwordx4 v[24:27], v[24:25], off
	global_load_dwordx4 v[40:43], v[32:33], off
	s_nop 0
	global_load_dwordx4 v[44:47], v[32:33], off offset:16
	v_mul_f32_e32 v19, s7, v8
	v_mul_f32_e32 v28, 0x3fb8aa3b, v19
	v_fma_f32 v29, v19, s17, -v28
	v_rndne_f32_e32 v30, v28
	v_fmac_f32_e32 v29, 0x32a5705f, v19
	v_sub_f32_e32 v28, v28, v30
	v_add_f32_e32 v28, v28, v29
	v_exp_f32_e32 v28, v28
	v_cvt_i32_f32_e32 v29, v30
	v_cmp_ngt_f32_e32 vcc, s21, v19
	s_lshl_b64 s[10:11], s[26:27], 6
	s_lshl_b32 s6, s6, 4
	v_ldexp_f32 v28, v28, v29
	v_cndmask_b32_e32 v28, 0, v28, vcc
	v_cmp_nlt_f32_e32 vcc, s22, v19
	s_or_b32 s6, s10, s6
	s_or_b32 s10, s6, s5
	v_cndmask_b32_e32 v19, v230, v28, vcc
	s_lshl_b64 s[6:7], s[10:11], 14
	s_add_i32 s4, s4, s76
	s_cmpk_gt_i32 s4, 0x1ff
	s_waitcnt vmcnt(2)
	v_lshlrev_b32_e32 v28, 16, v24
	v_and_b32_e32 v24, 0xffff0000, v24
	v_mul_f32_e32 v24, v19, v24
	v_mul_f32_e32 v28, v19, v28
	v_cvt_pk_bf16_f32 v24, v28, v24
	ds_write_b16 v9, v24 offset:32768
	ds_write_b16_d16_hi v9, v24 offset:33024
	v_lshlrev_b32_e32 v24, 16, v25
	v_mul_f32_e32 v24, v19, v24
	v_and_b32_e32 v25, 0xffff0000, v25
	v_mul_f32_e32 v25, v19, v25
	v_cvt_pk_bf16_f32 v24, v24, v25
	v_and_b32_e32 v25, 0xffff0000, v26
	v_mul_f32_e32 v25, v19, v25
	s_waitcnt vmcnt(1)
	ds_write_b16 v9, v40 offset:49152
	ds_write_b16_d16_hi v9, v40 offset:49408
	ds_write_b16 v9, v24 offset:33280
	ds_write_b16_d16_hi v9, v24 offset:33536
	ds_write_b16 v9, v41 offset:49664
	ds_write_b16_d16_hi v9, v41 offset:49920
	v_lshlrev_b32_e32 v24, 16, v26
	v_mul_f32_e32 v24, v19, v24
	v_cvt_pk_bf16_f32 v24, v24, v25
	ds_write_b16 v9, v24 offset:33792
	ds_write_b16_d16_hi v9, v24 offset:34048
	ds_write_b16 v9, v42 offset:50176
	ds_write_b16_d16_hi v9, v42 offset:50432
	v_lshlrev_b32_e32 v24, 16, v27
	v_mul_f32_e32 v24, v19, v24
	v_and_b32_e32 v25, 0xffff0000, v27
	v_mul_f32_e32 v25, v19, v25
	v_cvt_pk_bf16_f32 v24, v24, v25
	ds_write_b16 v9, v24 offset:34304
	ds_write_b16_d16_hi v9, v24 offset:34560
	ds_write_b16 v9, v43 offset:50688
	ds_write_b16_d16_hi v9, v43 offset:50944
	v_lshlrev_b32_e32 v24, 16, v20
	v_and_b32_e32 v20, 0xffff0000, v20
	v_mul_f32_e32 v20, v19, v20
	v_mul_f32_e32 v24, v19, v24
	v_cvt_pk_bf16_f32 v20, v24, v20
	ds_write_b16 v9, v20 offset:34816
	ds_write_b16_d16_hi v9, v20 offset:35072
	s_waitcnt vmcnt(0)
	ds_write_b16 v9, v44 offset:51200
	ds_write_b16_d16_hi v9, v44 offset:51456
	v_lshlrev_b32_e32 v20, 16, v21
	v_mul_f32_e32 v20, v19, v20
	v_and_b32_e32 v21, 0xffff0000, v21
	v_mul_f32_e32 v21, v19, v21
	v_cvt_pk_bf16_f32 v20, v20, v21
	ds_write_b16 v9, v20 offset:35328
	ds_write_b16_d16_hi v9, v20 offset:35584
	ds_write_b16 v9, v45 offset:51712
	ds_write_b16_d16_hi v9, v45 offset:51968
	v_lshlrev_b32_e32 v20, 16, v22
	v_mul_f32_e32 v20, v19, v20
	v_and_b32_e32 v21, 0xffff0000, v22
	v_mul_f32_e32 v21, v19, v21
	v_cvt_pk_bf16_f32 v20, v20, v21
	ds_write_b16 v9, v20 offset:35840
	ds_write_b16_d16_hi v9, v20 offset:36096
	ds_write_b16 v9, v46 offset:52224
	ds_write_b16_d16_hi v9, v46 offset:52480
	v_lshlrev_b32_e32 v20, 16, v23
	v_and_b32_e32 v21, 0xffff0000, v23
	v_mul_f32_e32 v20, v19, v20
	v_mul_f32_e32 v19, v19, v21
	v_cvt_pk_bf16_f32 v19, v20, v19
	ds_write_b16 v9, v19 offset:36352
	ds_write_b16_d16_hi v9, v19 offset:36608
	ds_write_b16 v9, v47 offset:52736
	ds_write_b16_d16_hi v9, v47 offset:52992
	s_cmpk_gt_i32 s4, 0x1ff
	s_cbranch_scc1 .Lrk_nopf0
	s_bfe_u32 vcc_lo, s4, 0x20004
	s_and_b32 s5, s4, 15
	s_ashr_i32 s26, s4, 6
	s_ashr_i32 s27, s26, 31
	s_lshl_b64 s[10:11], s[26:27], 13
	s_lshl_b32 s9, vcc_lo, 11
	s_lshl_b32 s30, s5, 7
	s_or_b32 s9, s10, s9
	s_or_b32 s10, s9, s30
	v_lshl_add_u64 v[68:69], s[10:11], 0, v[2:3]
	v_lshlrev_b64 v[68:69], 7, v[68:69]
	v_lshl_or_b32 v68, v4, 1, v68
	v_lshl_add_u64 v[70:71], s[14:15], 0, v[68:69]
	v_lshl_add_u64 v[68:69], s[0:1], 0, v[68:69]
	global_load_dwordx4 v[48:51], v[68:69], off offset:16
	global_load_dwordx4 v[52:55], v[68:69], off
	global_load_dwordx4 v[56:59], v[70:71], off
	global_load_dwordx4 v[60:63], v[70:71], off offset:16
; #define LAS __attribute__((address_space(3)))
; __device__ __forceinline__ void ret_stage(const Frame& F, int b, int h, int n, bool full, float lg) {
;     LAS unsigned char* L = F.lds;
;     const int tk = F.tid >> 2, part = F.tid & 3;
;     const size_t rowoff = (((size_t)b * 4 + h) * S + n * 128 + tk) * 64 + part * 16;
;     const u32x4* kp = (const u32x4*)((const bf16*)(F.ws + WS_PRK) + rowoff);
;     const u32x4* vp = (const u32x4*)((const bf16*)(F.ws + WS_PRV) + rowoff);
;     const u32x4 k0 = kp[0], k1 = kp[1], v0 = vp[0], v1 = vp[1];
;     if (full) { const u32x4* qp = (const u32x4*)((const bf16*)(F.ws + WS_PRQ) + rowoff);
;         const u32x4 q0 = qp[0], q1 = qp[1];
;         *(LAS u32x4*)(L + RL_Q + tk * 128 + part * 32) = q0; *(LAS u32x4*)(L + RL_Q + tk * 128 + part * 32 + 16) = q1;
;         *(LAS u32x4*)(L + RL_K + tk * 128 + part * 32) = k0; *(LAS u32x4*)(L + RL_K + tk * 128 + part * 32 + 16) = k1; }
;     const float kd = expf((float)(127 - tk) * lg);
;     const unsigned kw[8] = {k0.x, k0.y, k0.z, k0.w, k1.x, k1.y, k1.z, k1.w}, vw[8] = {v0.x, v0.y, v0.z, v0.w, v1.x, v1.y, v1.z, v1.w};
; #pragma unroll
;     for (int i = 0; i < 8; ++i) { const int d = part * 16 + 2 * i;
;         if (!full) { const unsigned pk = cvt_pk_bf16(bf2f((unsigned short)(kw[i] & 0xffffu)) * kd, bf2f((unsigned short)(kw[i] >> 16)) * kd);
; __device__ __forceinline__ void ret_kv_unit(const Frame& F, int unit) {
;     ...
;     const int fr = F.lane & 15, fq = F.lane >> 4, dtile = F.wave >> 1, et0 = (F.wave & 1) * 2;
;     f32x4 a0 = {0.f, 0.f, 0.f, 0.f}, a1 = {0.f, 0.f, 0.f, 0.f};
; #pragma unroll
;     for (int ks = 0; ks < 4; ++ks) {
;         const bf16x8 a = *(const LAS bf16x8*)(L + RL_KT + ((16 * dtile + fr) * 128 + 32 * ks + fq * 8) * 2);
;         const bf16x8 b0 = *(const LAS bf16x8*)(L + RL_VT + ((16 * et0 + fr) * 128 + 32 * ks + fq * 8) * 2);
;         const bf16x8 b1 = *(const LAS bf16x8*)(L + RL_VT + ((16 * (et0 + 1) + fr) * 128 + 32 * ks + fq * 8) * 2);
;         a0 = __builtin_amdgcn_mfma_f32_16x16x32_bf16(a, b0, a0, 0, 0, 0); a1 = __builtin_amdgcn_mfma_f32_16x16x32_bf16(a, b1, a1, 0, 0, 0);
;     }
;     float* kv = (float*)(F.ws + WS_KVB) + ((((size_t)b * 4 + h) * 16 + n) * 64) * 64;
; #pragma unroll
;     for (int j = 0; j < 4; ++j) { const int d = 16 * dtile + fq * 4 + j; kv[d * 64 + 16 * et0 + fr] = a0[j]; kv[d * 64 + 16 * (et0 + 1) + fr] = a1[j]; }
.Lrk_nopf0:
	s_waitcnt lgkmcnt(0)
	s_barrier
	ds_read_b128 v[20:23], v10 offset:32768
	ds_read_b128 v[24:27], v11 offset:49152
	ds_read_b128 v[28:31], v12 offset:49152
	s_waitcnt lgkmcnt(1)
	v_mfma_f32_16x16x32_bf16 v[24:27], v[20:23], v[24:27], 0
	s_waitcnt lgkmcnt(0)
	v_mfma_f32_16x16x32_bf16 v[20:23], v[20:23], v[28:31], 0
	ds_read_b128 v[28:31], v10 offset:32832
	ds_read_b128 v[32:35], v13 offset:49152
	ds_read_b128 v[36:39], v14 offset:49152
	s_waitcnt lgkmcnt(1)
	v_mfma_f32_16x16x32_bf16 v[24:27], v[28:31], v[32:35], v[24:27]
	s_waitcnt lgkmcnt(0)
	v_mfma_f32_16x16x32_bf16 v[20:23], v[28:31], v[36:39], v[20:23]
	ds_read_b128 v[28:31], v10 offset:32896
	ds_read_b128 v[32:35], v15 offset:49152
	ds_read_b128 v[36:39], v16 offset:49152
	s_waitcnt lgkmcnt(1)
	v_mfma_f32_16x16x32_bf16 v[24:27], v[28:31], v[32:35], v[24:27]
	s_waitcnt lgkmcnt(0)
	v_mfma_f32_16x16x32_bf16 v[20:23], v[28:31], v[36:39], v[20:23]
	ds_read_b128 v[28:31], v10 offset:32960
	ds_read_b128 v[32:35], v17 offset:49152
	ds_read_b128 v[36:39], v18 offset:49152
	s_waitcnt lgkmcnt(1)
	v_mfma_f32_16x16x32_bf16 v[24:27], v[28:31], v[32:35], v[24:27]
	s_waitcnt lgkmcnt(0)
	v_mfma_f32_16x16x32_bf16 v[20:23], v[28:31], v[36:39], v[20:23]
	v_lshl_add_u64 v[28:29], v[6:7], 0, s[6:7]
	s_nop 4
	global_store_dword v[28:29], v24, off
	s_nop 0
	global_store_dword v[28:29], v20, off offset:64
	global_store_dword v[28:29], v25, off offset:256
	global_store_dword v[28:29], v21, off offset:320
	global_store_dword v[28:29], v26, off offset:512
	global_store_dword v[28:29], v22, off offset:576
	global_store_dword v[28:29], v27, off offset:768
	global_store_dword v[28:29], v23, off offset:832
	v_mov_b32_e32 v24, v5
	s_cmpk_gt_i32 s4, 0x1ff
	s_cbranch_scc1 .Lrk_done
.Lrk_loop:
	s_bfe_u32 s6, s4, 0x20004
	s_and_b32 s5, s4, 15
	s_ashr_i32 s26, s4, 6
	s_lshl_b32 s7, s6, 2
	s_getpc_b64 s[10:11]
	s_add_u32 s10, s10, c_log_gamma@rel32@lo+4
	s_addc_u32 s11, s11, c_log_gamma@rel32@hi+12
	s_ashr_i32 s27, s26, 31
	s_load_dword s7, s[10:11], s7 offset:0x0
	s_waitcnt lgkmcnt(0)
	s_barrier
	s_waitcnt vmcnt(8)
	v_mov_b32_e32 v20, v48
	v_mov_b32_e32 v21, v49
	v_mov_b32_e32 v22, v50
	v_mov_b32_e32 v23, v51
	v_mov_b32_e32 v24, v52
	v_mov_b32_e32 v25, v53
	v_mov_b32_e32 v26, v54
	v_mov_b32_e32 v27, v55
	v_mov_b32_e32 v40, v56
	v_mov_b32_e32 v41, v57
	v_mov_b32_e32 v42, v58
	v_mov_b32_e32 v43, v59
	v_mov_b32_e32 v44, v60
	v_mov_b32_e32 v45, v61
	v_mov_b32_e32 v46, v62
	v_mov_b32_e32 v47, v63
	v_mul_f32_e32 v19, s7, v8
	v_mul_f32_e32 v28, 0x3fb8aa3b, v19
	v_fma_f32 v29, v19, s17, -v28
	v_rndne_f32_e32 v30, v28
	v_fmac_f32_e32 v29, 0x32a5705f, v19
	v_sub_f32_e32 v28, v28, v30
	v_add_f32_e32 v28, v28, v29
	v_exp_f32_e32 v28, v28
	v_cvt_i32_f32_e32 v29, v30
	v_cmp_ngt_f32_e32 vcc, s21, v19
	s_lshl_b64 s[10:11], s[26:27], 6
	s_lshl_b32 s6, s6, 4
	v_ldexp_f32 v28, v28, v29
	v_cndmask_b32_e32 v28, 0, v28, vcc
	v_cmp_nlt_f32_e32 vcc, s22, v19
	s_or_b32 s6, s10, s6
	s_or_b32 s10, s6, s5
	v_cndmask_b32_e32 v19, v230, v28, vcc
	s_lshl_b64 s[6:7], s[10:11], 14
	s_add_i32 s4, s4, s76
	s_cmpk_gt_i32 s4, 0x1ff
	v_lshlrev_b32_e32 v28, 16, v24
	v_and_b32_e32 v24, 0xffff0000, v24
	v_mul_f32_e32 v24, v19, v24
	v_mul_f32_e32 v28, v19, v28
	v_cvt_pk_bf16_f32 v24, v28, v24
	ds_write_b16 v9, v24 offset:32768
	ds_write_b16_d16_hi v9, v24 offset:33024
	v_lshlrev_b32_e32 v24, 16, v25
	v_mul_f32_e32 v24, v19, v24
	v_and_b32_e32 v25, 0xffff0000, v25
	v_mul_f32_e32 v25, v19, v25
	v_cvt_pk_bf16_f32 v24, v24, v25
	v_and_b32_e32 v25, 0xffff0000, v26
	v_mul_f32_e32 v25, v19, v25
	ds_write_b16 v9, v40 offset:49152
	ds_write_b16_d16_hi v9, v40 offset:49408
	ds_write_b16 v9, v24 offset:33280
	ds_write_b16_d16_hi v9, v24 offset:33536
	ds_write_b16 v9, v41 offset:49664
	ds_write_b16_d16_hi v9, v41 offset:49920
	v_lshlrev_b32_e32 v24, 16, v26
	v_mul_f32_e32 v24, v19, v24
	v_cvt_pk_bf16_f32 v24, v24, v25
	ds_write_b16 v9, v24 offset:33792
	ds_write_b16_d16_hi v9, v24 offset:34048
	ds_write_b16 v9, v42 offset:50176
	ds_write_b16_d16_hi v9, v42 offset:50432
	v_lshlrev_b32_e32 v24, 16, v27
	v_mul_f32_e32 v24, v19, v24
	v_and_b32_e32 v25, 0xffff0000, v27
	v_mul_f32_e32 v25, v19, v25
	v_cvt_pk_bf16_f32 v24, v24, v25
	ds_write_b16 v9, v24 offset:34304
	ds_write_b16_d16_hi v9, v24 offset:34560
	ds_write_b16 v9, v43 offset:50688
	ds_write_b16_d16_hi v9, v43 offset:50944
	v_lshlrev_b32_e32 v24, 16, v20
	v_and_b32_e32 v20, 0xffff0000, v20
	v_mul_f32_e32 v20, v19, v20
	v_mul_f32_e32 v24, v19, v24
	v_cvt_pk_bf16_f32 v20, v24, v20
	ds_write_b16 v9, v20 offset:34816
	ds_write_b16_d16_hi v9, v20 offset:35072
	ds_write_b16 v9, v44 offset:51200
	ds_write_b16_d16_hi v9, v44 offset:51456
	v_lshlrev_b32_e32 v20, 16, v21
	v_mul_f32_e32 v20, v19, v20
	v_and_b32_e32 v21, 0xffff0000, v21
	v_mul_f32_e32 v21, v19, v21
	v_cvt_pk_bf16_f32 v20, v20, v21
	ds_write_b16 v9, v20 offset:35328
	ds_write_b16_d16_hi v9, v20 offset:35584
	ds_write_b16 v9, v45 offset:51712
	ds_write_b16_d16_hi v9, v45 offset:51968
	v_lshlrev_b32_e32 v20, 16, v22
	v_mul_f32_e32 v20, v19, v20
	v_and_b32_e32 v21, 0xffff0000, v22
	v_mul_f32_e32 v21, v19, v21
	v_cvt_pk_bf16_f32 v20, v20, v21
	ds_write_b16 v9, v20 offset:35840
	ds_write_b16_d16_hi v9, v20 offset:36096
	ds_write_b16 v9, v46 offset:52224
	ds_write_b16_d16_hi v9, v46 offset:52480
	v_lshlrev_b32_e32 v20, 16, v23
	v_and_b32_e32 v21, 0xffff0000, v23
	v_mul_f32_e32 v20, v19, v20
	v_mul_f32_e32 v19, v19, v21
	v_cvt_pk_bf16_f32 v19, v20, v19
	ds_write_b16 v9, v19 offset:36352
	ds_write_b16_d16_hi v9, v19 offset:36608
	ds_write_b16 v9, v47 offset:52736
	ds_write_b16_d16_hi v9, v47 offset:52992
	s_cmpk_gt_i32 s4, 0x1ff
	s_cbranch_scc1 .Lrk_nopf1
	s_bfe_u32 vcc_lo, s4, 0x20004
	s_and_b32 s5, s4, 15
	s_ashr_i32 s26, s4, 6
	s_ashr_i32 s27, s26, 31
	s_lshl_b64 s[10:11], s[26:27], 13
	s_lshl_b32 s9, vcc_lo, 11
	s_lshl_b32 s30, s5, 7
	s_or_b32 s9, s10, s9
	s_or_b32 s10, s9, s30
	v_lshl_add_u64 v[68:69], s[10:11], 0, v[2:3]
	v_lshlrev_b64 v[68:69], 7, v[68:69]
	v_lshl_or_b32 v68, v4, 1, v68
	v_lshl_add_u64 v[70:71], s[14:15], 0, v[68:69]
	v_lshl_add_u64 v[68:69], s[0:1], 0, v[68:69]
	global_load_dwordx4 v[48:51], v[68:69], off offset:16
	global_load_dwordx4 v[52:55], v[68:69], off
	global_load_dwordx4 v[56:59], v[70:71], off
	global_load_dwordx4 v[60:63], v[70:71], off offset:16
; #define LAS __attribute__((address_space(3)))
; __device__ __forceinline__ void ret_kv_unit(const Frame& F, int unit) {
;     ...
;     const int fr = F.lane & 15, fq = F.lane >> 4, dtile = F.wave >> 1, et0 = (F.wave & 1) * 2;
;     f32x4 a0 = {0.f, 0.f, 0.f, 0.f}, a1 = {0.f, 0.f, 0.f, 0.f};
; #pragma unroll
;     for (int ks = 0; ks < 4; ++ks) {
;         const bf16x8 a = *(const LAS bf16x8*)(L + RL_KT + ((16 * dtile + fr) * 128 + 32 * ks + fq * 8) * 2);
;         const bf16x8 b0 = *(const LAS bf16x8*)(L + RL_VT + ((16 * et0 + fr) * 128 + 32 * ks + fq * 8) * 2);
;         const bf16x8 b1 = *(const LAS bf16x8*)(L + RL_VT + ((16 * (et0 + 1) + fr) * 128 + 32 * ks + fq * 8) * 2);
;         a0 = __builtin_amdgcn_mfma_f32_16x16x32_bf16(a, b0, a0, 0, 0, 0); a1 = __builtin_amdgcn_mfma_f32_16x16x32_bf16(a, b1, a1, 0, 0, 0);
;     }
;     float* kv = (float*)(F.ws + WS_KVB) + ((((size_t)b * 4 + h) * 16 + n) * 64) * 64;
; #pragma unroll
;     for (int j = 0; j < 4; ++j) { const int d = 16 * dtile + fq * 4 + j; kv[d * 64 + 16 * et0 + fr] = a0[j]; kv[d * 64 + 16 * (et0 + 1) + fr] = a1[j]; }
; __device__ __forceinline__ void gates_tiles(const Frame& F, int l, int wg0) {
;     const int NGW = (F.G - wg0) * NWAVES, gw = NGW - 1 - ((F.bid - wg0) * NWAVES + F.wave), fr = F.lane & 15, fq = F.lane >> 4;
;     const bf16* H = (const bf16*)(F.ws + WS_H); const bf16* WG = (const bf16*)(F.ws + WS_WIN) + ((size_t)l * NINP + 3072) * D;
;     for (int rt = gw; rt < T / 16; rt += NGW) {
;         f32x4 a0 = {0.f, 0.f, 0.f, 0.f}, a1 = {0.f, 0.f, 0.f, 0.f};
;         const bf16* ap = H + (size_t)(16 * rt + fr) * D + 8 * fq; const bf16* bp = WG + (size_t)fr * D + 8 * fq;
.Lrk_nopf1:
	s_waitcnt lgkmcnt(0)
	s_barrier
	ds_read_b128 v[20:23], v10 offset:32768
	ds_read_b128 v[24:27], v11 offset:49152
	ds_read_b128 v[28:31], v12 offset:49152
	s_waitcnt lgkmcnt(1)
	v_mfma_f32_16x16x32_bf16 v[24:27], v[20:23], v[24:27], 0
	s_waitcnt lgkmcnt(0)
	v_mfma_f32_16x16x32_bf16 v[20:23], v[20:23], v[28:31], 0
	ds_read_b128 v[28:31], v10 offset:32832
	ds_read_b128 v[32:35], v13 offset:49152
	ds_read_b128 v[36:39], v14 offset:49152
	s_waitcnt lgkmcnt(1)
	v_mfma_f32_16x16x32_bf16 v[24:27], v[28:31], v[32:35], v[24:27]
	s_waitcnt lgkmcnt(0)
	v_mfma_f32_16x16x32_bf16 v[20:23], v[28:31], v[36:39], v[20:23]
	ds_read_b128 v[28:31], v10 offset:32896
	ds_read_b128 v[32:35], v15 offset:49152
	ds_read_b128 v[36:39], v16 offset:49152
	s_waitcnt lgkmcnt(1)
	v_mfma_f32_16x16x32_bf16 v[24:27], v[28:31], v[32:35], v[24:27]
	s_waitcnt lgkmcnt(0)
	v_mfma_f32_16x16x32_bf16 v[20:23], v[28:31], v[36:39], v[20:23]
	ds_read_b128 v[28:31], v10 offset:32960
	ds_read_b128 v[32:35], v17 offset:49152
	ds_read_b128 v[36:39], v18 offset:49152
	s_waitcnt lgkmcnt(1)
	v_mfma_f32_16x16x32_bf16 v[24:27], v[28:31], v[32:35], v[24:27]
	s_waitcnt lgkmcnt(0)
	v_mfma_f32_16x16x32_bf16 v[20:23], v[28:31], v[36:39], v[20:23]
	v_lshl_add_u64 v[28:29], v[6:7], 0, s[6:7]
	s_nop 4
	global_store_dword v[28:29], v24, off
	s_nop 0
	global_store_dword v[28:29], v20, off offset:64
	global_store_dword v[28:29], v25, off offset:256
	global_store_dword v[28:29], v21, off offset:320
	global_store_dword v[28:29], v26, off offset:512
	global_store_dword v[28:29], v22, off offset:576
	global_store_dword v[28:29], v27, off offset:768
	global_store_dword v[28:29], v23, off offset:832
	v_mov_b32_e32 v24, v5
	s_cmpk_gt_i32 s4, 0x1ff
	s_cbranch_scc0 .Lrk_loop
.Lrk_done:
.LBB0_1336:
	s_not_b32 s0, s3
	s_add_i32 s3, s75, s0
	s_cmpk_gt_i32 s3, 0x3ff
	s_barrier
	s_cbranch_scc1 .LBB0_1345
	v_and_b32_e32 v198, 48, v1
	v_lshl_add_u64 v[2:3], s[78:79], 0, v[198:199]
	s_mov_b64 s[4:5], 0x6f000000
	s_waitcnt vmcnt(27)
	v_lshl_add_u64 v[10:11], v[2:3], 0, s[4:5]
	v_readlane_b32 s4, v249, 28
	v_cmp_gt_u32_e64 s[0:1], 32, v1
	v_lshlrev_b32_e32 v2, 11, v5
	s_waitcnt vmcnt(20)
	v_add_u32_e32 v1, s4, v24
	s_lshl_b32 s4, s8, 4
	v_subrev_u32_e32 v14, s4, v1
	v_readlane_b32 s4, v249, 39
	v_mov_b32_e32 v3, v199
	v_readlane_b32 s5, v249, 40
	v_and_b32_e32 v198, 48, v0
	v_lshl_add_u64 v[12:13], s[78:79], 0, v[198:199]
	v_lshl_add_u64 v[2:3], s[4:5], 0, v[2:3]
	v_lshl_add_u64 v[2:3], v[2:3], 0, v[198:199]
	v_lshl_add_u64 v[16:17], s[78:79], 0, v[2:3]
	s_branch .LBB0_1339
